# code placement: one s_nop ahead of three K-loop heads so every GEMM K-loop head has the baseline's byte phase (mod 8)
# speedup vs baseline: 1.0305x; 1.0019x over previous
; #define PG8_STAGE(bufoff, gbase, voff) do { _Pragma("unroll") for (int _i = 0; _i < 2; ++_i) \
;         __builtin_amdgcn_global_load_lds((const unsigned*)((const char*)(gbase) + (voff)[_i]), (LAS unsigned*)(lds + (bufoff) + ldsw + _i * 8192), 16, 0, 0); } while (0)
; #define PG8_WAIT_V(n) asm volatile("s_waitcnt vmcnt(" #n ")" ::: "memory")
; #define PG8_BAR __builtin_amdgcn_s_barrier()
; template <class Epi, class Sched, bool ZERO>
; __device__ __forceinline__ void gemm_phase_acc(LAS unsigned char* lds, const Gemm g, const Sched& S, const Epi& E, f32x4 (&acc)[2][2][4][2]) {
;     ...
;     if constexpr (ZERO) {
; #pragma unroll
;     for (int a = 0; a < 2; ++a)
; #pragma unroll
;         for (int b = 0; b < 2; ++b)
; #pragma unroll
;             for (int m = 0; m < 4; ++m)
; #pragma unroll
;                 for (int n = 0; n < 2; ++n) acc[a][b][m][n] = (f32x4){0.f, 0.f, 0.f, 0.f};
;     }
;     ...
;     PG8_STAGE(PG8_SB(0, 0), cB, voffB); PG8_STAGE(PG8_SA(0, 0), cA, voffA); PG8_STAGE(PG8_SB(0, 1), cB + hstep, voffB); PG8_STAGE(PG8_SA(0, 1), cA + hstep, voffA);
;     if (wr == 1) PG8_BAR;
;     PG8_WAIT_V(4); PG8_BAR;
;     PG8_STAGE(PG8_SB(1, 0), cB + kstep, voffB); PG8_STAGE(PG8_SA(1, 0), cA + kstep, voffA); PG8_STAGE(PG8_SB(1, 1), cB + hstep + kstep, voffB);
;     PG8_WAIT_V(6); PG8_BAR;
.LBB0_526:
	v_lshrrev_b32_e32 v16, 1, v11
	v_and_b32_e32 v140, 24, v16
	s_lshl_b32 s6, s6, 5
	v_and_b32_e32 v15, 15, v11
	v_lshlrev_b32_e32 v16, 1, v140
	v_lshlrev_b32_e32 v11, 2, v11
	s_and_b32 s38, s6, 0x60
	v_lshl_or_b32 v144, s7, 6, v15
	v_lshl_or_b32 v15, v15, 6, v16
	s_lshl_b32 s7, s7, 13
	v_and_b32_e32 v11, 32, v11
	s_lshl_b32 s6, s38, 7
	v_bitop3_b32 v16, v15, s7, v11 bitop3:0xde
	v_bitop3_b32 v11, v15, s6, v11 bitop3:0xde
	s_mov_b64 s[6:7], 0x80
	s_add_i32 m0, s25, 0x18000
	v_lshl_add_u64 v[6:7], v[6:7], 0, s[6:7]
	s_waitcnt vmcnt(4)
	s_barrier
	global_load_lds_dwordx4 v[6:7], off
	v_lshl_add_u64 v[4:5], v[4:5], 0, s[6:7]
	s_add_i32 m0, s25, 0x1a000
	s_add_i32 s39, s25, 0x8000
	s_add_i32 s40, s25, 0xa000
	global_load_lds_dwordx4 v[4:5], off
	v_lshl_add_u64 v[2:3], v[2:3], 0, s[6:7]
	s_mov_b32 m0, s39
	s_add_u32 s46, s0, 0x20080
	global_load_lds_dwordx4 v[2:3], off
	v_lshl_add_u64 v[0:1], v[0:1], 0, s[6:7]
	s_mov_b32 m0, s40
	s_addc_u32 s47, s1, 0
	global_load_lds_dwordx4 v[0:1], off
	s_add_i32 m0, s25, 0x1c000
	v_lshl_add_u64 v[0:1], s[46:47], 0, v[132:133]
	global_load_lds_dwordx4 v[0:1], off
	v_lshl_add_u64 v[0:1], s[46:47], 0, v[128:129]
	s_add_i32 m0, s25, 0x1e000
	s_add_u32 s10, s70, s10
	global_load_lds_dwordx4 v[0:1], off
	v_lshlrev_b32_e32 v0, 13, v13
	v_and_b32_e32 v0, 0xffffc000, v0
	v_lshl_add_u32 v0, v12, 10, v0
	v_and_b32_e32 v1, 1, v13
	v_lshl_or_b32 v0, v1, 6, v0
	s_addc_u32 s11, s71, s11
	v_lshl_add_u32 v0, v14, 1, v0
	v_mov_b32_e32 v1, v133
	v_lshl_add_u64 v[0:1], s[10:11], 0, v[0:1]
	s_mov_b64 s[46:47], 0xac20080
	v_lshl_add_u64 v[136:137], v[0:1], 0, s[46:47]
	v_lshlrev_b32_e32 v0, 13, v8
	v_and_b32_e32 v0, 0xffffc000, v0
	v_lshl_add_u32 v0, v9, 10, v0
	v_and_b32_e32 v1, 1, v8
	s_add_u32 s41, s70, s42
	v_lshl_or_b32 v0, v1, 6, v0
	s_addc_u32 s42, s71, 0
	s_waitcnt vmcnt(6)
	v_lshl_add_u32 v0, v10, 1, v0
	v_mov_b32_e32 v1, v133
	s_add_u32 s41, s41, 0x2000100
	v_lshl_add_u64 v[0:1], s[10:11], 0, v[0:1]
	s_addc_u32 s48, s42, 0
	s_add_i32 s52, s35, s44
	s_add_i32 s54, s22, s44
	s_add_i32 s56, s23, s44
	s_add_i32 s58, s33, s44
	v_lshl_add_u64 v[138:139], v[0:1], 0, s[46:47]
	s_mov_b32 s49, -2
	s_mov_b64 s[42:43], 0
	v_add_u32_e32 v141, s35, v11
	v_add_u32_e32 v142, 0, v16
	s_add_i32 s50, s25, 0xc000
	s_add_i32 s51, s25, 0xe000
	v_add_u32_e32 v143, s22, v11
	s_add_i32 s53, s52, 0x2000
	s_add_i32 s55, s54, 0x2000
	v_add_u32_e32 v145, s23, v11
	v_add_u32_e32 v146, s33, v11
	s_add_i32 s57, s56, 0x2000
	s_add_i32 s59, s58, 0x2000
	v_mov_b32_e32 v0, v133
	v_mov_b32_e32 v1, v133
	v_mov_b32_e32 v2, v133
	v_mov_b32_e32 v3, v133
	v_mov_b32_e32 v4, v133
	v_mov_b32_e32 v5, v133
	v_mov_b32_e32 v6, v133
	v_mov_b32_e32 v7, v133
	v_mov_b32_e32 v12, v133
	v_mov_b32_e32 v13, v133
	v_mov_b32_e32 v14, v133
	v_mov_b32_e32 v15, v133
	v_mov_b32_e32 v20, v133
	v_mov_b32_e32 v21, v133
	v_mov_b32_e32 v22, v133
	v_mov_b32_e32 v23, v133
	v_mov_b32_e32 v28, v133
	v_mov_b32_e32 v29, v133
	v_mov_b32_e32 v30, v133
	v_mov_b32_e32 v31, v133
	v_mov_b32_e32 v36, v133
	v_mov_b32_e32 v37, v133
	v_mov_b32_e32 v38, v133
	v_mov_b32_e32 v39, v133
	v_mov_b32_e32 v44, v133
	v_mov_b32_e32 v45, v133
	v_mov_b32_e32 v46, v133
	v_mov_b32_e32 v47, v133
	v_mov_b32_e32 v52, v133
	v_mov_b32_e32 v53, v133
	v_mov_b32_e32 v54, v133
	v_mov_b32_e32 v55, v133
	v_mov_b32_e32 v8, v133
	v_mov_b32_e32 v9, v133
	v_mov_b32_e32 v10, v133
	v_mov_b32_e32 v11, v133
	v_mov_b32_e32 v16, v133
	v_mov_b32_e32 v17, v133
	v_mov_b32_e32 v18, v133
	v_mov_b32_e32 v19, v133
	v_mov_b32_e32 v24, v133
	v_mov_b32_e32 v25, v133
	v_mov_b32_e32 v26, v133
	v_mov_b32_e32 v27, v133
	v_mov_b32_e32 v32, v133
	v_mov_b32_e32 v33, v133
	v_mov_b32_e32 v34, v133
	v_mov_b32_e32 v35, v133
	v_mov_b32_e32 v40, v133
	v_mov_b32_e32 v41, v133
	v_mov_b32_e32 v42, v133
	v_mov_b32_e32 v43, v133
	v_mov_b32_e32 v48, v133
	v_mov_b32_e32 v49, v133
	v_mov_b32_e32 v50, v133
	v_mov_b32_e32 v51, v133
	v_mov_b32_e32 v56, v133
	v_mov_b32_e32 v57, v133
	v_mov_b32_e32 v58, v133
	v_mov_b32_e32 v59, v133
	v_mov_b32_e32 v60, v133
	v_mov_b32_e32 v61, v133
	v_mov_b32_e32 v62, v133
	v_mov_b32_e32 v63, v133
	v_mov_b32_e32 v64, v133
	v_mov_b32_e32 v65, v133
	v_mov_b32_e32 v66, v133
	v_mov_b32_e32 v67, v133
	v_mov_b32_e32 v68, v133
	v_mov_b32_e32 v69, v133
	v_mov_b32_e32 v70, v133
	v_mov_b32_e32 v71, v133
	v_mov_b32_e32 v72, v133
	v_mov_b32_e32 v73, v133
	v_mov_b32_e32 v74, v133
	v_mov_b32_e32 v75, v133
	v_mov_b32_e32 v76, v133
	v_mov_b32_e32 v77, v133
	v_mov_b32_e32 v78, v133
	v_mov_b32_e32 v79, v133
	v_mov_b32_e32 v80, v133
	v_mov_b32_e32 v81, v133
	v_mov_b32_e32 v82, v133
	v_mov_b32_e32 v83, v133
	v_mov_b32_e32 v88, v133
	v_mov_b32_e32 v89, v133
	v_mov_b32_e32 v90, v133
	v_mov_b32_e32 v91, v133
	v_mov_b32_e32 v96, v133
	v_mov_b32_e32 v97, v133
	v_mov_b32_e32 v98, v133
	v_mov_b32_e32 v99, v133
	v_mov_b32_e32 v104, v133
	v_mov_b32_e32 v105, v133
	v_mov_b32_e32 v106, v133
	v_mov_b32_e32 v107, v133
	v_mov_b32_e32 v84, v133
	v_mov_b32_e32 v85, v133
	v_mov_b32_e32 v86, v133
	v_mov_b32_e32 v87, v133
	v_mov_b32_e32 v92, v133
	v_mov_b32_e32 v93, v133
	v_mov_b32_e32 v94, v133
	v_mov_b32_e32 v95, v133
	v_mov_b32_e32 v100, v133
	v_mov_b32_e32 v101, v133
	v_mov_b32_e32 v102, v133
	v_mov_b32_e32 v103, v133
	v_mov_b32_e32 v108, v133
	v_mov_b32_e32 v109, v133
	v_mov_b32_e32 v110, v133
	v_mov_b32_e32 v111, v133
	v_mov_b32_e32 v112, v133
	v_mov_b32_e32 v113, v133
	v_mov_b32_e32 v114, v133
	v_mov_b32_e32 v115, v133
	v_mov_b32_e32 v116, v133
	v_mov_b32_e32 v117, v133
	v_mov_b32_e32 v118, v133
	v_mov_b32_e32 v119, v133
	v_mov_b32_e32 v120, v133
	v_mov_b32_e32 v121, v133
	v_mov_b32_e32 v122, v133
	v_mov_b32_e32 v123, v133
	v_mov_b32_e32 v124, v133
	v_mov_b32_e32 v125, v133
	v_mov_b32_e32 v126, v133
	v_mov_b32_e32 v127, v133
	s_barrier
	s_nop 0

; #define PG8_STAGE(bufoff, gbase, voff) do { _Pragma("unroll") for (int _i = 0; _i < 2; ++_i) \
;         __builtin_amdgcn_global_load_lds((const unsigned*)((const char*)(gbase) + (voff)[_i]), (LAS unsigned*)(lds + (bufoff) + ldsw + _i * 8192), 16, 0, 0); } while (0)
; #define PG8_WAIT_V(n) asm volatile("s_waitcnt vmcnt(" #n ")" ::: "memory")
; #define PG8_BAR __builtin_amdgcn_s_barrier()
; template <class Epi, class Sched, bool ZERO>
; __device__ __forceinline__ void gemm_phase_acc(LAS unsigned char* lds, const Gemm g, const Sched& S, const Epi& E, f32x4 (&acc)[2][2][4][2]) {
;     ...
;     if constexpr (ZERO) {
; #pragma unroll
;     for (int a = 0; a < 2; ++a)
; #pragma unroll
;         for (int b = 0; b < 2; ++b)
; #pragma unroll
;             for (int m = 0; m < 4; ++m)
; #pragma unroll
;                 for (int n = 0; n < 2; ++n) acc[a][b][m][n] = (f32x4){0.f, 0.f, 0.f, 0.f};
;     }
;     ...
;     PG8_STAGE(PG8_SB(0, 0), cB, voffB); PG8_STAGE(PG8_SA(0, 0), cA, voffA); PG8_STAGE(PG8_SB(0, 1), cB + hstep, voffB); PG8_STAGE(PG8_SA(0, 1), cA + hstep, voffA);
;     if (wr == 1) PG8_BAR;
;     PG8_WAIT_V(4); PG8_BAR;
;     PG8_STAGE(PG8_SB(1, 0), cB + kstep, voffB); PG8_STAGE(PG8_SA(1, 0), cA + kstep, voffA); PG8_STAGE(PG8_SB(1, 1), cB + hstep + kstep, voffB);
;     PG8_WAIT_V(6); PG8_BAR;
.LBB0_972:
	v_and_b32_e32 v14, 15, v140
	v_and_b32_e32 v15, 48, v140
	v_lshl_or_b32 v14, v14, 6, v15
	v_lshlrev_b32_e32 v15, 2, v140
	s_and_b32 s28, s4, 3
	s_lshl_b32 s4, s17, 13
	v_and_b32_e32 v15, 32, v15
	v_bitop3_b32 v16, v14, s4, v15 bitop3:0xde
	s_lshl_b32 s4, s28, 12
	v_bitop3_b32 v14, v14, s4, v15 bitop3:0xde
	s_mov_b64 s[4:5], 0x80
	s_add_i32 m0, s19, 0x18000
	v_lshl_add_u64 v[6:7], v[6:7], 0, s[4:5]
	s_waitcnt vmcnt(4)
	s_barrier
	global_load_lds_dwordx4 v[6:7], off
	v_lshl_add_u64 v[4:5], v[4:5], 0, s[4:5]
	s_add_i32 m0, s19, 0x1a000
	s_add_i32 s29, s19, 0x8000
	s_add_i32 s30, s19, 0xa000
	global_load_lds_dwordx4 v[4:5], off
	v_lshl_add_u64 v[2:3], v[2:3], 0, s[4:5]
	s_mov_b32 m0, s29
	s_add_u32 s14, s0, 0x20080
	global_load_lds_dwordx4 v[2:3], off
	v_lshl_add_u64 v[0:1], v[0:1], 0, s[4:5]
	s_mov_b32 m0, s30
	s_addc_u32 s15, s1, 0
	global_load_lds_dwordx4 v[0:1], off
	s_add_i32 m0, s19, 0x1c000
	v_lshl_add_u64 v[0:1], s[14:15], 0, v[132:133]
	global_load_lds_dwordx4 v[0:1], off
	v_lshl_add_u64 v[0:1], s[14:15], 0, v[128:129]
	s_add_i32 m0, s19, 0x1e000
	s_add_u32 s6, s70, s6
	global_load_lds_dwordx4 v[0:1], off
	v_lshlrev_b32_e32 v0, 13, v12
	v_and_b32_e32 v0, 0xffffc000, v0
	v_lshl_add_u32 v0, v11, 10, v0
	v_and_b32_e32 v1, 1, v12
	v_lshl_or_b32 v0, v1, 6, v0
	s_addc_u32 s7, s71, s7
	v_lshl_add_u32 v0, v13, 1, v0
	v_mov_b32_e32 v1, v133
	v_lshl_add_u64 v[0:1], s[6:7], 0, v[0:1]
	s_mov_b64 s[14:15], 0x9420080
	v_lshl_add_u64 v[136:137], v[0:1], 0, s[14:15]
	v_lshlrev_b32_e32 v0, 13, v8
	v_and_b32_e32 v0, 0xffffc000, v0
	v_lshl_add_u32 v0, v9, 10, v0
	v_and_b32_e32 v1, 1, v8
	s_add_u32 s8, s70, s8
	v_lshl_or_b32 v0, v1, 6, v0
	s_addc_u32 s9, s71, 0
	s_waitcnt vmcnt(6)
	v_lshl_add_u32 v0, v10, 1, v0
	v_mov_b32_e32 v1, v133
	s_add_u32 s31, s8, 0x2600100
	v_lshl_add_u64 v[0:1], s[6:7], 0, v[0:1]
	s_addc_u32 s38, s9, 0
	s_add_i32 s42, s35, s10
	s_add_i32 s44, s22, s10
	s_add_i32 s46, s23, s10
	s_add_i32 s48, s33, s10
	v_lshl_add_u64 v[138:139], v[0:1], 0, s[14:15]
	s_mov_b32 s39, -2
	s_mov_b64 s[8:9], 0
	v_add_u32_e32 v141, s35, v14
	v_add_u32_e32 v142, 0, v16
	s_add_i32 s40, s19, 0xc000
	s_add_i32 s41, s19, 0xe000
	v_add_u32_e32 v143, s22, v14
	s_add_i32 s43, s42, 0x2000
	s_add_i32 s45, s44, 0x2000
	v_add_u32_e32 v144, s23, v14
	v_add_u32_e32 v145, s33, v14
	s_add_i32 s47, s46, 0x2000
	s_add_i32 s49, s48, 0x2000
	v_mov_b32_e32 v0, v133
	v_mov_b32_e32 v1, v133
	v_mov_b32_e32 v2, v133
	v_mov_b32_e32 v3, v133
	v_mov_b32_e32 v4, v133
	v_mov_b32_e32 v5, v133
	v_mov_b32_e32 v6, v133
	v_mov_b32_e32 v7, v133
	v_mov_b32_e32 v8, v133
	v_mov_b32_e32 v9, v133
	v_mov_b32_e32 v10, v133
	v_mov_b32_e32 v11, v133
	v_mov_b32_e32 v28, v133
	v_mov_b32_e32 v29, v133
	v_mov_b32_e32 v30, v133
	v_mov_b32_e32 v31, v133
	v_mov_b32_e32 v32, v133
	v_mov_b32_e32 v33, v133
	v_mov_b32_e32 v34, v133
	v_mov_b32_e32 v35, v133
	v_mov_b32_e32 v36, v133
	v_mov_b32_e32 v37, v133
	v_mov_b32_e32 v38, v133
	v_mov_b32_e32 v39, v133
	v_mov_b32_e32 v48, v133
	v_mov_b32_e32 v49, v133
	v_mov_b32_e32 v50, v133
	v_mov_b32_e32 v51, v133
	v_mov_b32_e32 v52, v133
	v_mov_b32_e32 v53, v133
	v_mov_b32_e32 v54, v133
	v_mov_b32_e32 v55, v133
	v_mov_b32_e32 v56, v133
	v_mov_b32_e32 v57, v133
	v_mov_b32_e32 v58, v133
	v_mov_b32_e32 v59, v133
	v_mov_b32_e32 v68, v133
	v_mov_b32_e32 v69, v133
	v_mov_b32_e32 v70, v133
	v_mov_b32_e32 v71, v133
	v_mov_b32_e32 v76, v133
	v_mov_b32_e32 v77, v133
	v_mov_b32_e32 v78, v133
	v_mov_b32_e32 v79, v133
	v_mov_b32_e32 v84, v133
	v_mov_b32_e32 v85, v133
	v_mov_b32_e32 v86, v133
	v_mov_b32_e32 v87, v133
	v_mov_b32_e32 v92, v133
	v_mov_b32_e32 v93, v133
	v_mov_b32_e32 v94, v133
	v_mov_b32_e32 v95, v133
	v_mov_b32_e32 v100, v133
	v_mov_b32_e32 v101, v133
	v_mov_b32_e32 v102, v133
	v_mov_b32_e32 v103, v133
	v_mov_b32_e32 v120, v133
	v_mov_b32_e32 v121, v133
	v_mov_b32_e32 v122, v133
	v_mov_b32_e32 v123, v133
	v_mov_b32_e32 v112, v133
	v_mov_b32_e32 v113, v133
	v_mov_b32_e32 v114, v133
	v_mov_b32_e32 v115, v133
	v_mov_b32_e32 v72, v133
	v_mov_b32_e32 v73, v133
	v_mov_b32_e32 v74, v133
	v_mov_b32_e32 v75, v133
	v_mov_b32_e32 v80, v133
	v_mov_b32_e32 v81, v133
	v_mov_b32_e32 v82, v133
	v_mov_b32_e32 v83, v133
	v_mov_b32_e32 v88, v133
	v_mov_b32_e32 v89, v133
	v_mov_b32_e32 v90, v133
	v_mov_b32_e32 v91, v133
	v_mov_b32_e32 v96, v133
	v_mov_b32_e32 v97, v133
	v_mov_b32_e32 v98, v133
	v_mov_b32_e32 v99, v133
	v_mov_b32_e32 v116, v133
	v_mov_b32_e32 v117, v133
	v_mov_b32_e32 v118, v133
	v_mov_b32_e32 v119, v133
	v_mov_b32_e32 v124, v133
	v_mov_b32_e32 v125, v133
	v_mov_b32_e32 v126, v133
	v_mov_b32_e32 v127, v133
	v_mov_b32_e32 v108, v133
	v_mov_b32_e32 v109, v133
	v_mov_b32_e32 v110, v133
	v_mov_b32_e32 v111, v133
	v_mov_b32_e32 v104, v133
	v_mov_b32_e32 v105, v133
	v_mov_b32_e32 v106, v133
	v_mov_b32_e32 v107, v133
	v_mov_b32_e32 v64, v133
	v_mov_b32_e32 v65, v133
	v_mov_b32_e32 v66, v133
	v_mov_b32_e32 v67, v133
	v_mov_b32_e32 v60, v133
	v_mov_b32_e32 v61, v133
	v_mov_b32_e32 v62, v133
	v_mov_b32_e32 v63, v133
	v_mov_b32_e32 v44, v133
	v_mov_b32_e32 v45, v133
	v_mov_b32_e32 v46, v133
	v_mov_b32_e32 v47, v133
	v_mov_b32_e32 v40, v133
	v_mov_b32_e32 v41, v133
	v_mov_b32_e32 v42, v133
	v_mov_b32_e32 v43, v133
	v_mov_b32_e32 v24, v133
	v_mov_b32_e32 v25, v133
	v_mov_b32_e32 v26, v133
	v_mov_b32_e32 v27, v133
	v_mov_b32_e32 v20, v133
	v_mov_b32_e32 v21, v133
	v_mov_b32_e32 v22, v133
	v_mov_b32_e32 v23, v133
	v_mov_b32_e32 v16, v133
	v_mov_b32_e32 v17, v133
	v_mov_b32_e32 v18, v133
	v_mov_b32_e32 v19, v133
	v_mov_b32_e32 v12, v133
	v_mov_b32_e32 v13, v133
	v_mov_b32_e32 v14, v133
	v_mov_b32_e32 v15, v133
	s_barrier
	s_nop 0

; #define PG8_STAGE(bufoff, gbase, voff) do { _Pragma("unroll") for (int _i = 0; _i < 2; ++_i) \
;         __builtin_amdgcn_global_load_lds((const unsigned*)((const char*)(gbase) + (voff)[_i]), (LAS unsigned*)(lds + (bufoff) + ldsw + _i * 8192), 16, 0, 0); } while (0)
; #define PG8_WAIT_V(n) asm volatile("s_waitcnt vmcnt(" #n ")" ::: "memory")
; #define PG8_BAR __builtin_amdgcn_s_barrier()
; template <class Epi, class Sched, bool ZERO>
; __device__ __forceinline__ void gemm_phase_acc(LAS unsigned char* lds, const Gemm g, const Sched& S, const Epi& E, f32x4 (&acc)[2][2][4][2]) {
;     ...
;     if constexpr (ZERO) {
; #pragma unroll
;     for (int a = 0; a < 2; ++a)
; #pragma unroll
;         for (int b = 0; b < 2; ++b)
; #pragma unroll
;             for (int m = 0; m < 4; ++m)
; #pragma unroll
;                 for (int n = 0; n < 2; ++n) acc[a][b][m][n] = (f32x4){0.f, 0.f, 0.f, 0.f};
;     }
;     ...
;     PG8_STAGE(PG8_SB(0, 0), cB, voffB); PG8_STAGE(PG8_SA(0, 0), cA, voffA); PG8_STAGE(PG8_SB(0, 1), cB + hstep, voffB); PG8_STAGE(PG8_SA(0, 1), cA + hstep, voffA);
;     if (wr == 1) PG8_BAR;
;     PG8_WAIT_V(4); PG8_BAR;
;     PG8_STAGE(PG8_SB(1, 0), cB + kstep, voffB); PG8_STAGE(PG8_SA(1, 0), cA + kstep, voffA); PG8_STAGE(PG8_SB(1, 1), cB + hstep + kstep, voffB);
;     PG8_WAIT_V(6); PG8_BAR;
.LBB0_1036:
	v_bfe_u32 v210, v224, 4, 2
	v_and_b32_e32 v140, 15, v224
	v_lshlrev_b32_e32 v14, 4, v210
	v_lshlrev_b32_e32 v15, 2, v224
	s_and_b32 s13, s4, 3
	v_lshl_or_b32 v14, v140, 6, v14
	s_lshl_b32 s4, s12, 13
	v_and_b32_e32 v15, 32, v15
	v_bitop3_b32 v16, v14, s4, v15 bitop3:0xde
	s_lshl_b32 s4, s13, 12
	v_bitop3_b32 v14, v14, s4, v15 bitop3:0xde
	s_mov_b64 s[4:5], 0x80
	s_add_i32 m0, s15, 0x18000
	v_lshl_add_u64 v[6:7], v[6:7], 0, s[4:5]
	s_lshl_b32 s17, s12, 6
	s_waitcnt vmcnt(4)
	s_barrier
	global_load_lds_dwordx4 v[6:7], off
	v_lshl_add_u64 v[4:5], v[4:5], 0, s[4:5]
	s_add_i32 m0, s15, 0x1a000
	s_add_i32 s26, s15, 0x8000
	s_add_i32 s27, s15, 0xa000
	global_load_lds_dwordx4 v[4:5], off
	v_lshl_add_u64 v[2:3], v[2:3], 0, s[4:5]
	s_mov_b32 m0, s26
	s_add_u32 s6, s0, 0x40080
	global_load_lds_dwordx4 v[2:3], off
	v_lshl_add_u64 v[0:1], v[0:1], 0, s[4:5]
	s_mov_b32 m0, s27
	s_addc_u32 s7, s1, 0
	global_load_lds_dwordx4 v[0:1], off
	s_add_i32 m0, s15, 0x1c000
	v_lshl_add_u64 v[0:1], s[6:7], 0, v[132:133]
	global_load_lds_dwordx4 v[0:1], off
	v_lshl_add_u64 v[0:1], s[6:7], 0, v[128:129]
	s_add_i32 m0, s15, 0x1e000
	v_readlane_b32 s6, v254, 26
	global_load_lds_dwordx4 v[0:1], off
	v_lshlrev_b32_e32 v0, 14, v12
	v_and_b32_e32 v0, 0xffff8000, v0
	v_lshl_add_u32 v0, v11, 11, v0
	v_and_b32_e32 v1, 1, v12
	v_lshl_or_b32 v0, v1, 6, v0
	v_readlane_b32 s7, v254, 27
	s_add_u32 s6, s70, s6
	v_lshl_add_u32 v0, v13, 1, v0
	v_mov_b32_e32 v1, v133
	s_addc_u32 s7, s71, s7
	v_lshl_add_u64 v[0:1], s[6:7], 0, v[0:1]
	s_mov_b64 s[10:11], 0x7440080
	v_lshl_add_u64 v[136:137], v[0:1], 0, s[10:11]
	v_lshlrev_b32_e32 v0, 14, v8
	v_and_b32_e32 v0, 0xffff8000, v0
	v_lshl_add_u32 v0, v9, 11, v0
	v_and_b32_e32 v1, 1, v8
	v_lshl_or_b32 v0, v1, 6, v0
	v_lshl_add_u32 v0, v10, 1, v0
	v_mov_b32_e32 v1, v133
	v_lshl_add_u64 v[0:1], s[6:7], 0, v[0:1]
	s_add_u32 s6, s70, s19
	s_addc_u32 s7, s71, 0
	s_waitcnt vmcnt(6)
	s_add_u32 s19, s6, 0x2700100
	s_addc_u32 s28, s7, 0
	v_add_u32_e32 v141, s35, v14
	v_add_u32_e32 v143, s22, v14
	s_add_i32 s35, s35, s8
	s_add_i32 s22, s22, s8
	v_add_u32_e32 v144, s23, v14
	v_add_u32_e32 v145, s33, v14
	s_add_i32 s23, s23, s8
	s_add_i32 s33, s33, s8
	v_or_b32_e32 v227, s17, v140
	v_lshl_add_u64 v[138:139], v[0:1], 0, s[10:11]
	s_mov_b32 s29, -2
	s_mov_b64 s[6:7], 0
	v_add_u32_e32 v142, 0, v16
	s_add_i32 s30, s15, 0xc000
	s_add_i32 s31, s15, 0xe000
	s_add_i32 s38, s35, 0x2000
	s_add_i32 s39, s22, 0x2000
	s_add_i32 s40, s23, 0x2000
	s_add_i32 s41, s33, 0x2000
	v_mov_b32_e32 v0, v133
	v_mov_b32_e32 v1, v133
	v_mov_b32_e32 v2, v133
	v_mov_b32_e32 v3, v133
	v_mov_b32_e32 v4, v133
	v_mov_b32_e32 v5, v133
	v_mov_b32_e32 v6, v133
	v_mov_b32_e32 v7, v133
	v_mov_b32_e32 v16, v133
	v_mov_b32_e32 v17, v133
	v_mov_b32_e32 v18, v133
	v_mov_b32_e32 v19, v133
	v_mov_b32_e32 v20, v133
	v_mov_b32_e32 v21, v133
	v_mov_b32_e32 v22, v133
	v_mov_b32_e32 v23, v133
	v_mov_b32_e32 v32, v133
	v_mov_b32_e32 v33, v133
	v_mov_b32_e32 v34, v133
	v_mov_b32_e32 v35, v133
	v_mov_b32_e32 v36, v133
	v_mov_b32_e32 v37, v133
	v_mov_b32_e32 v38, v133
	v_mov_b32_e32 v39, v133
	v_mov_b32_e32 v48, v133
	v_mov_b32_e32 v49, v133
	v_mov_b32_e32 v50, v133
	v_mov_b32_e32 v51, v133
	v_mov_b32_e32 v52, v133
	v_mov_b32_e32 v53, v133
	v_mov_b32_e32 v54, v133
	v_mov_b32_e32 v55, v133
	v_mov_b32_e32 v8, v133
	v_mov_b32_e32 v9, v133
	v_mov_b32_e32 v10, v133
	v_mov_b32_e32 v11, v133
	v_mov_b32_e32 v12, v133
	v_mov_b32_e32 v13, v133
	v_mov_b32_e32 v14, v133
	v_mov_b32_e32 v15, v133
	v_mov_b32_e32 v24, v133
	v_mov_b32_e32 v25, v133
	v_mov_b32_e32 v26, v133
	v_mov_b32_e32 v27, v133
	v_mov_b32_e32 v28, v133
	v_mov_b32_e32 v29, v133
	v_mov_b32_e32 v30, v133
	v_mov_b32_e32 v31, v133
	v_mov_b32_e32 v40, v133
	v_mov_b32_e32 v41, v133
	v_mov_b32_e32 v42, v133
	v_mov_b32_e32 v43, v133
	v_mov_b32_e32 v44, v133
	v_mov_b32_e32 v45, v133
	v_mov_b32_e32 v46, v133
	v_mov_b32_e32 v47, v133
	v_mov_b32_e32 v56, v133
	v_mov_b32_e32 v57, v133
	v_mov_b32_e32 v58, v133
	v_mov_b32_e32 v59, v133
	v_mov_b32_e32 v60, v133
	v_mov_b32_e32 v61, v133
	v_mov_b32_e32 v62, v133
	v_mov_b32_e32 v63, v133
	v_mov_b32_e32 v64, v133
	v_mov_b32_e32 v65, v133
	v_mov_b32_e32 v66, v133
	v_mov_b32_e32 v67, v133
	v_mov_b32_e32 v68, v133
	v_mov_b32_e32 v69, v133
	v_mov_b32_e32 v70, v133
	v_mov_b32_e32 v71, v133
	v_mov_b32_e32 v80, v133
	v_mov_b32_e32 v81, v133
	v_mov_b32_e32 v82, v133
	v_mov_b32_e32 v83, v133
	v_mov_b32_e32 v84, v133
	v_mov_b32_e32 v85, v133
	v_mov_b32_e32 v86, v133
	v_mov_b32_e32 v87, v133
	v_mov_b32_e32 v96, v133
	v_mov_b32_e32 v97, v133
	v_mov_b32_e32 v98, v133
	v_mov_b32_e32 v99, v133
	v_mov_b32_e32 v100, v133
	v_mov_b32_e32 v101, v133
	v_mov_b32_e32 v102, v133
	v_mov_b32_e32 v103, v133
	v_mov_b32_e32 v112, v133
	v_mov_b32_e32 v113, v133
	v_mov_b32_e32 v114, v133
	v_mov_b32_e32 v115, v133
	v_mov_b32_e32 v116, v133
	v_mov_b32_e32 v117, v133
	v_mov_b32_e32 v118, v133
	v_mov_b32_e32 v119, v133
	v_mov_b32_e32 v72, v133
	v_mov_b32_e32 v73, v133
	v_mov_b32_e32 v74, v133
	v_mov_b32_e32 v75, v133
	v_mov_b32_e32 v76, v133
	v_mov_b32_e32 v77, v133
	v_mov_b32_e32 v78, v133
	v_mov_b32_e32 v79, v133
	v_mov_b32_e32 v88, v133
	v_mov_b32_e32 v89, v133
	v_mov_b32_e32 v90, v133
	v_mov_b32_e32 v91, v133
	v_mov_b32_e32 v92, v133
	v_mov_b32_e32 v93, v133
	v_mov_b32_e32 v94, v133
	v_mov_b32_e32 v95, v133
	v_mov_b32_e32 v104, v133
	v_mov_b32_e32 v105, v133
	v_mov_b32_e32 v106, v133
	v_mov_b32_e32 v107, v133
	v_mov_b32_e32 v108, v133
	v_mov_b32_e32 v109, v133
	v_mov_b32_e32 v110, v133
	v_mov_b32_e32 v111, v133
	v_mov_b32_e32 v120, v133
	v_mov_b32_e32 v121, v133
	v_mov_b32_e32 v122, v133
	v_mov_b32_e32 v123, v133
	v_mov_b32_e32 v124, v133
	v_mov_b32_e32 v125, v133
	v_mov_b32_e32 v126, v133
	v_mov_b32_e32 v127, v133
	s_barrier
	s_nop 0
